# L1 in-proj K-loop: first K-tile after an epilogue skips its two vmcnt(8) (they only waited for epilogue store acks)
# speedup vs baseline: 1.0119x; 1.0032x over previous
; #define PG8_STAGE(bufoff, gbase, voff) do { _Pragma("unroll") for (int _i = 0; _i < 2; ++_i) \
;         __builtin_amdgcn_global_load_lds((const unsigned*)((const char*)(gbase) + (voff)[_i]), (PG8_LAS unsigned*)(lds + (bufoff) + ldsw + _i * 8192), 16, 0, 0); } while (0)
; #define PG8_LDA(dst, b, h) do { _Pragma("unroll") for (int m = 0; m < 4; ++m) _Pragma("unroll") for (int k = 0; k < 2; ++k) dst[m][k] = *(const PG8_LAS bf16x8*)(lds + PG8_SA(b, h) + aoff + m * 2048 + k * 1024); } while (0)
; #define PG8_LDB(dst, b, h) do { _Pragma("unroll") for (int n = 0; n < 2; ++n) _Pragma("unroll") for (int k = 0; k < 2; ++k) dst[n][k] = *(const PG8_LAS bf16x8*)(lds + PG8_SB(b, h) + boff + n * 2048 + k * 1024); } while (0)
; #define PG8_SCHED __builtin_amdgcn_sched_barrier(0)
; template <class Epi, class Sched, bool ALIGN_EPI = false, bool SP2 = false>
; __device__ __forceinline__ void gemm_phase(PG8_LAS unsigned char* lds, const Gemm g, const Sched& S, const Epi& E) {
;     ...
;         const char* nA = has_next ? (const char*)g.A + (size_t)nxt.pm * tstep : cA; const char* nB = has_next ? (const char*)g.Bt + (size_t)nxt.pn * tstep : cB;
;         for (int t = 0; t < nt; t += 2) {
;             const bool last = (t == nt - 2);
;             const char* a1 = cA + (size_t)(t + 1) * kstep;
;             const char* a2 = last ? nA : cA + (size_t)(t + 2) * kstep; const char* b2 = last ? nB : cB + (size_t)(t + 2) * kstep;
;             const char* a3 = a2 + kstep; const char* b3 = b2 + kstep;
;             if (last && has_next) S.a_ready(nxt);
;             if constexpr (SP2) {
;             PG8_LDB(B0, 0, 0); PG8_LDB(B1, 0, 1); PG8_SCHED; PG8_LDA(At, 0, 0); PG8_STAGE(PG8_SA(1, 1), a1 + hstep, voffA);
;     ...
; #pragma unroll
;         for (int a = 0; a < 2; ++a)
; #pragma unroll
;             for (int b = 0; b < 2; ++b)
; #pragma unroll
;                 for (int m = 0; m < 4; ++m)
; #pragma unroll
;                     for (int n = 0; n < 2; ++n) acc[a][b][m][n] = (f32x4){0.f, 0.f, 0.f, 0.f};
.LBB0_125:
	s_ashr_i32 s15, s14, 31
	s_lshl_b64 s[18:19], s[14:15], 19
	s_add_u32 s18, s23, s18
	s_addc_u32 s19, s26, s19
	s_and_b64 s[20:21], s[0:1], exec
	s_cselect_b32 s15, s19, s3
	s_cselect_b32 s36, s18, s2
	s_ashr_i32 s13, s12, 31
	s_lshl_b64 s[20:21], s[12:13], 19
	s_add_u32 s28, s52, s20
	s_addc_u32 s29, s53, s21
	s_and_b64 s[20:21], s[0:1], exec
	s_cselect_b32 s13, s29, s5
	s_cselect_b32 s37, s28, s4
	s_add_u32 s2, s2, 0x40080
	s_addc_u32 s3, s3, 0
	s_add_u32 s45, s4, 0x100
	v_mov_b32_e32 v2, 0
	s_addc_u32 s46, s5, 0
	s_mov_b32 s47, -2
	v_mov_b32_e32 v3, v2
	v_mov_b32_e32 v4, v2
	v_mov_b32_e32 v5, v2
	v_mov_b32_e32 v6, v2
	v_mov_b32_e32 v7, v2
	v_mov_b32_e32 v8, v2
	v_mov_b32_e32 v9, v2
	v_mov_b32_e32 v18, v2
	v_mov_b32_e32 v19, v2
	v_mov_b32_e32 v20, v2
	v_mov_b32_e32 v21, v2
	v_mov_b32_e32 v22, v2
	v_mov_b32_e32 v23, v2
	v_mov_b32_e32 v24, v2
	v_mov_b32_e32 v25, v2
	v_mov_b32_e32 v34, v2
	v_mov_b32_e32 v35, v2
	v_mov_b32_e32 v36, v2
	v_mov_b32_e32 v37, v2
	v_mov_b32_e32 v38, v2
	v_mov_b32_e32 v39, v2
	v_mov_b32_e32 v40, v2
	v_mov_b32_e32 v41, v2
	s_waitcnt vmcnt(0)
	v_mov_b32_e32 v50, v2
	v_mov_b32_e32 v51, v2
	v_mov_b32_e32 v52, v2
	v_mov_b32_e32 v53, v2
	v_mov_b32_e32 v54, v2
	v_mov_b32_e32 v55, v2
	v_mov_b32_e32 v56, v2
	v_mov_b32_e32 v57, v2
	v_mov_b32_e32 v10, v2
	v_mov_b32_e32 v11, v2
	v_mov_b32_e32 v12, v2
	v_mov_b32_e32 v13, v2
	v_mov_b32_e32 v14, v2
	v_mov_b32_e32 v15, v2
	v_mov_b32_e32 v16, v2
	v_mov_b32_e32 v17, v2
	v_mov_b32_e32 v26, v2
	v_mov_b32_e32 v27, v2
	v_mov_b32_e32 v28, v2
	v_mov_b32_e32 v29, v2
	v_mov_b32_e32 v30, v2
	v_mov_b32_e32 v31, v2
	v_mov_b32_e32 v32, v2
	v_mov_b32_e32 v33, v2
	v_mov_b32_e32 v42, v2
	v_mov_b32_e32 v43, v2
	v_mov_b32_e32 v44, v2
	v_mov_b32_e32 v45, v2
	v_mov_b32_e32 v46, v2
	v_mov_b32_e32 v47, v2
	v_mov_b32_e32 v48, v2
	v_mov_b32_e32 v49, v2
	v_mov_b32_e32 v58, v2
	v_mov_b32_e32 v59, v2
	v_mov_b32_e32 v60, v2
	v_mov_b32_e32 v61, v2
	v_mov_b32_e32 v62, v2
	v_mov_b32_e32 v63, v2
	v_mov_b32_e32 v64, v2
	v_mov_b32_e32 v65, v2
	v_mov_b32_e32 v66, v2
	v_mov_b32_e32 v67, v2
	v_mov_b32_e32 v68, v2
	v_mov_b32_e32 v69, v2
	v_mov_b32_e32 v70, v2
	v_mov_b32_e32 v71, v2
	v_mov_b32_e32 v72, v2
	v_mov_b32_e32 v73, v2
	v_mov_b32_e32 v82, v2
	v_mov_b32_e32 v83, v2
	v_mov_b32_e32 v84, v2
	v_mov_b32_e32 v85, v2
	v_mov_b32_e32 v86, v2
	v_mov_b32_e32 v87, v2
	v_mov_b32_e32 v88, v2
	v_mov_b32_e32 v89, v2
	v_mov_b32_e32 v98, v2
	v_mov_b32_e32 v99, v2
	v_mov_b32_e32 v100, v2
	v_mov_b32_e32 v101, v2
	v_mov_b32_e32 v102, v2
	v_mov_b32_e32 v103, v2
	v_mov_b32_e32 v104, v2
	v_mov_b32_e32 v105, v2
	v_mov_b32_e32 v114, v2
	v_mov_b32_e32 v115, v2
	v_mov_b32_e32 v116, v2
	v_mov_b32_e32 v117, v2
	v_mov_b32_e32 v118, v2
	v_mov_b32_e32 v119, v2
	v_mov_b32_e32 v120, v2
	v_mov_b32_e32 v121, v2
	v_mov_b32_e32 v74, v2
	v_mov_b32_e32 v75, v2
	v_mov_b32_e32 v76, v2
	v_mov_b32_e32 v77, v2
	v_mov_b32_e32 v78, v2
	v_mov_b32_e32 v79, v2
	v_mov_b32_e32 v80, v2
	v_mov_b32_e32 v81, v2
	v_mov_b32_e32 v90, v2
	v_mov_b32_e32 v91, v2
	v_mov_b32_e32 v92, v2
	v_mov_b32_e32 v93, v2
	v_mov_b32_e32 v94, v2
	v_mov_b32_e32 v95, v2
	v_mov_b32_e32 v96, v2
	v_mov_b32_e32 v97, v2
	v_mov_b32_e32 v106, v2
	v_mov_b32_e32 v107, v2
	v_mov_b32_e32 v108, v2
	v_mov_b32_e32 v109, v2
	v_mov_b32_e32 v110, v2
	v_mov_b32_e32 v111, v2
	v_mov_b32_e32 v112, v2
	v_mov_b32_e32 v113, v2
	v_mov_b32_e32 v122, v2
	v_mov_b32_e32 v123, v2
	v_mov_b32_e32 v124, v2
	v_mov_b32_e32 v125, v2
	v_mov_b32_e32 v126, v2
	v_mov_b32_e32 v127, v2
	v_mov_b32_e32 v128, v2
	v_mov_b32_e32 v129, v2
	s_cmp_gt_u32 s44, 1
	s_cselect_b32 s100, 1, 0
.LBB0_126:
	s_add_u32 s4, s2, 0xfffc0080
	s_addc_u32 s5, s3, -1
	s_add_i32 s48, 0, 0x10000
	s_cmp_eq_u32 s47, 12
	s_cselect_b32 s21, s15, s5
	s_cselect_b32 s20, s36, s4
	v_add_u32_e32 v150, s48, v147
	s_cselect_b32 s5, s13, s46
	s_cselect_b32 s4, s37, s45
	s_add_i32 s50, 0, 0x14000
	ds_read_b128 v[168:171], v150
	ds_read_b128 v[172:175], v150 offset:1024
	ds_read_b128 v[176:179], v150 offset:2048
	ds_read_b128 v[180:183], v150 offset:3072
	v_add_u32_e32 v150, s50, v147
	ds_read_b128 v[184:187], v150
	ds_read_b128 v[196:199], v150 offset:1024
	ds_read_b128 v[200:203], v150 offset:2048
	ds_read_b128 v[204:207], v150 offset:3072
	v_lshl_add_u64 v[150:151], s[2:3], 0, v[164:165]
	s_add_i32 m0, s31, 0xc000
	ds_read_b128 v[208:211], v163
	ds_read_b128 v[212:215], v163 offset:1024
	ds_read_b128 v[216:219], v163 offset:2048
	ds_read_b128 v[220:223], v163 offset:3072
	ds_read_b128 v[224:227], v163 offset:4096
	ds_read_b128 v[228:231], v163 offset:5120
	ds_read_b128 v[232:235], v163 offset:6144
	ds_read_b128 v[236:239], v163 offset:7168
	global_load_lds_dwordx4 v[150:151], off
	v_lshl_add_u64 v[150:151], s[2:3], 0, v[166:167]
	s_add_i32 m0, s31, 0xe000
	s_nop 0
	global_load_lds_dwordx4 v[150:151], off
	s_cmp_lg_u32 s100, 0
	s_cbranch_scc1 .Lkw_l1in_a
	s_waitcnt vmcnt(8)
; #define PG8_STAGE(bufoff, gbase, voff) do { _Pragma("unroll") for (int _i = 0; _i < 2; ++_i) \
;         __builtin_amdgcn_global_load_lds((const unsigned*)((const char*)(gbase) + (voff)[_i]), (PG8_LAS unsigned*)(lds + (bufoff) + ldsw + _i * 8192), 16, 0, 0); } while (0)
; #define PG8_LDA(dst, b, h) do { _Pragma("unroll") for (int m = 0; m < 4; ++m) _Pragma("unroll") for (int k = 0; k < 2; ++k) dst[m][k] = *(const PG8_LAS bf16x8*)(lds + PG8_SA(b, h) + aoff + m * 2048 + k * 1024); } while (0)
; #define PG8_LDB(dst, b, h) do { _Pragma("unroll") for (int n = 0; n < 2; ++n) _Pragma("unroll") for (int k = 0; k < 2; ++k) dst[n][k] = *(const PG8_LAS bf16x8*)(lds + PG8_SB(b, h) + boff + n * 2048 + k * 1024); } while (0)
; #define PG8_MMA(ai, bj, At, Bt) do { __builtin_amdgcn_s_setprio(1); _Pragma("unroll") for (int m = 0; m < 4; ++m) _Pragma("unroll") for (int n = 0; n < 2; ++n) _Pragma("unroll") for (int k = 0; k < 2; ++k) \
;         acc[ai][bj][m][n] = __builtin_amdgcn_mfma_f32_16x16x32_bf16(Bt[n][k], At[m][k], acc[ai][bj][m][n], 0, 0, 0); __builtin_amdgcn_s_setprio(0); } while (0)
; #define PG8_WAIT_V(n) asm volatile("s_waitcnt vmcnt(" #n ")" ::: "memory")
; #define PG8_WAIT_L(n) asm volatile("s_waitcnt lgkmcnt(" #n ")" ::: "memory")
; #define PG8_BAR __builtin_amdgcn_s_barrier()
; #define PG8_SCHED __builtin_amdgcn_sched_barrier(0)
; template <class Epi, class Sched, bool ALIGN_EPI = false, bool SP2 = false>
; __device__ __forceinline__ void gemm_phase(PG8_LAS unsigned char* lds, const Gemm g, const Sched& S, const Epi& E) {
;     ...
;             PG8_LDB(B0, 0, 0); PG8_LDB(B1, 0, 1); PG8_SCHED; PG8_LDA(At, 0, 0); PG8_STAGE(PG8_SA(1, 1), a1 + hstep, voffA);
;             PG8_WAIT_V(8); PG8_WAIT_L(0); PG8_BAR; PG8_MMA(0, 0, At, B0); PG8_MMA(0, 1, At, B1); PG8_BAR; PG8_SCHED;
;             PG8_LDA(At, 0, 1); PG8_STAGE(PG8_SB(0, 0), b2, voffB); PG8_STAGE(PG8_SB(0, 1), b2 + hstep, voffB); PG8_STAGE(PG8_SA(0, 0), a2, voffA);
;             PG8_WAIT_V(8); PG8_WAIT_L(0); PG8_BAR; PG8_MMA(1, 0, At, B0); PG8_MMA(1, 1, At, B1); PG8_BAR; PG8_SCHED;
.Lkw_l1in_a:
	s_waitcnt lgkmcnt(0)
	s_barrier
	s_setprio 1
	s_waitcnt lgkmcnt(0)
	v_mfma_f32_16x16x32_bf16 v[126:129], v[168:171], v[208:211], v[126:129]
	v_mfma_f32_16x16x32_bf16 v[122:125], v[176:179], v[208:211], v[122:125]
	v_mfma_f32_16x16x32_bf16 v[110:113], v[168:171], v[216:219], v[110:113]
	v_mfma_f32_16x16x32_bf16 v[106:109], v[176:179], v[216:219], v[106:109]
	v_mfma_f32_16x16x32_bf16 v[94:97], v[168:171], v[224:227], v[94:97]
	v_mfma_f32_16x16x32_bf16 v[90:93], v[176:179], v[224:227], v[90:93]
	v_mfma_f32_16x16x32_bf16 v[78:81], v[168:171], v[232:235], v[78:81]
	v_mfma_f32_16x16x32_bf16 v[74:77], v[176:179], v[232:235], v[74:77]
	v_mfma_f32_16x16x32_bf16 v[126:129], v[172:175], v[212:215], v[126:129]
	v_mfma_f32_16x16x32_bf16 v[122:125], v[180:183], v[212:215], v[122:125]
	v_mfma_f32_16x16x32_bf16 v[110:113], v[172:175], v[220:223], v[110:113]
	v_mfma_f32_16x16x32_bf16 v[106:109], v[180:183], v[220:223], v[106:109]
	v_mfma_f32_16x16x32_bf16 v[94:97], v[172:175], v[228:231], v[94:97]
	v_mfma_f32_16x16x32_bf16 v[90:93], v[180:183], v[228:231], v[90:93]
	v_mfma_f32_16x16x32_bf16 v[78:81], v[172:175], v[236:239], v[78:81]
	v_mfma_f32_16x16x32_bf16 v[74:77], v[180:183], v[236:239], v[74:77]
	s_setprio 0
	s_setprio 1
	v_mfma_f32_16x16x32_bf16 v[118:121], v[184:187], v[208:211], v[118:121]
	v_mfma_f32_16x16x32_bf16 v[114:117], v[200:203], v[208:211], v[114:117]
	v_mfma_f32_16x16x32_bf16 v[102:105], v[184:187], v[216:219], v[102:105]
	v_mfma_f32_16x16x32_bf16 v[98:101], v[200:203], v[216:219], v[98:101]
	v_mfma_f32_16x16x32_bf16 v[86:89], v[184:187], v[224:227], v[86:89]
	v_mfma_f32_16x16x32_bf16 v[82:85], v[200:203], v[224:227], v[82:85]
	v_mfma_f32_16x16x32_bf16 v[70:73], v[184:187], v[232:235], v[70:73]
	v_mfma_f32_16x16x32_bf16 v[66:69], v[200:203], v[232:235], v[66:69]
	v_mfma_f32_16x16x32_bf16 v[118:121], v[196:199], v[212:215], v[118:121]
	v_mfma_f32_16x16x32_bf16 v[114:117], v[204:207], v[212:215], v[114:117]
	v_mfma_f32_16x16x32_bf16 v[102:105], v[196:199], v[220:223], v[102:105]
	v_mfma_f32_16x16x32_bf16 v[98:101], v[204:207], v[220:223], v[98:101]
	v_mfma_f32_16x16x32_bf16 v[86:89], v[196:199], v[228:231], v[86:89]
	v_mfma_f32_16x16x32_bf16 v[82:85], v[204:207], v[228:231], v[82:85]
	v_mfma_f32_16x16x32_bf16 v[70:73], v[196:199], v[236:239], v[70:73]
	v_mfma_f32_16x16x32_bf16 v[66:69], v[204:207], v[236:239], v[66:69]
	s_setprio 0
	s_barrier
	s_add_i32 s48, s48, s30
	v_lshl_add_u64 v[150:151], s[4:5], 0, v[134:135]
	s_mov_b32 m0, s48
	ds_read_b128 v[208:211], v163 offset:16384
	ds_read_b128 v[212:215], v163 offset:17408
	ds_read_b128 v[216:219], v163 offset:18432
	ds_read_b128 v[220:223], v163 offset:19456
	ds_read_b128 v[224:227], v163 offset:20480
	ds_read_b128 v[228:231], v163 offset:21504
	ds_read_b128 v[232:235], v163 offset:22528
	ds_read_b128 v[236:239], v163 offset:23552
	global_load_lds_dwordx4 v[150:151], off
	s_add_i32 m0, s48, 0x2000
	s_add_u32 s48, s4, 0x40000
	v_lshl_add_u64 v[152:153], s[4:5], 0, v[130:131]
	s_addc_u32 s49, s5, 0
	s_add_i32 s50, s50, s30
	global_load_lds_dwordx4 v[152:153], off
	v_lshl_add_u64 v[154:155], s[48:49], 0, v[134:135]
	s_mov_b32 m0, s50
	v_lshl_add_u64 v[156:157], s[20:21], 0, v[132:133]
	global_load_lds_dwordx4 v[154:155], off
	v_lshl_add_u64 v[154:155], s[48:49], 0, v[130:131]
	s_add_i32 m0, s50, 0x2000
	s_nop 0
	global_load_lds_dwordx4 v[154:155], off
	v_lshl_add_u64 v[154:155], s[20:21], 0, v[136:137]
	s_mov_b32 m0, s31
	s_nop 0
	global_load_lds_dwordx4 v[154:155], off
	s_mov_b32 m0, s38
	s_nop 0
	global_load_lds_dwordx4 v[156:157], off
	s_cmp_lg_u32 s100, 0
	s_cbranch_scc1 .Lkw_l1in_b
	s_waitcnt vmcnt(8)
.Lkw_l1in_b:
	s_mov_b32 s100, 0
	s_waitcnt lgkmcnt(0)
	s_barrier
	s_setprio 1
	s_waitcnt lgkmcnt(0)
	v_mfma_f32_16x16x32_bf16 v[62:65], v[168:171], v[208:211], v[62:65]
	v_mfma_f32_16x16x32_bf16 v[58:61], v[176:179], v[208:211], v[58:61]
	v_mfma_f32_16x16x32_bf16 v[46:49], v[168:171], v[216:219], v[46:49]
	v_mfma_f32_16x16x32_bf16 v[42:45], v[176:179], v[216:219], v[42:45]
	v_mfma_f32_16x16x32_bf16 v[30:33], v[168:171], v[224:227], v[30:33]
	v_mfma_f32_16x16x32_bf16 v[26:29], v[176:179], v[224:227], v[26:29]
	v_mfma_f32_16x16x32_bf16 v[14:17], v[168:171], v[232:235], v[14:17]
	v_mfma_f32_16x16x32_bf16 v[10:13], v[176:179], v[232:235], v[10:13]
	v_mfma_f32_16x16x32_bf16 v[62:65], v[172:175], v[212:215], v[62:65]
	v_mfma_f32_16x16x32_bf16 v[58:61], v[180:183], v[212:215], v[58:61]
	v_mfma_f32_16x16x32_bf16 v[46:49], v[172:175], v[220:223], v[46:49]
	v_mfma_f32_16x16x32_bf16 v[42:45], v[180:183], v[220:223], v[42:45]
	v_mfma_f32_16x16x32_bf16 v[30:33], v[172:175], v[228:231], v[30:33]
	v_mfma_f32_16x16x32_bf16 v[26:29], v[180:183], v[228:231], v[26:29]
	v_mfma_f32_16x16x32_bf16 v[14:17], v[172:175], v[236:239], v[14:17]
	v_mfma_f32_16x16x32_bf16 v[10:13], v[180:183], v[236:239], v[10:13]
	s_setprio 0
	s_setprio 1
	v_mfma_f32_16x16x32_bf16 v[54:57], v[184:187], v[208:211], v[54:57]
	v_mfma_f32_16x16x32_bf16 v[50:53], v[200:203], v[208:211], v[50:53]
	v_mfma_f32_16x16x32_bf16 v[38:41], v[184:187], v[216:219], v[38:41]
	v_mfma_f32_16x16x32_bf16 v[34:37], v[200:203], v[216:219], v[34:37]
	v_mfma_f32_16x16x32_bf16 v[22:25], v[184:187], v[224:227], v[22:25]
	v_mfma_f32_16x16x32_bf16 v[18:21], v[200:203], v[224:227], v[18:21]
	v_mfma_f32_16x16x32_bf16 v[6:9], v[184:187], v[232:235], v[6:9]
	v_mfma_f32_16x16x32_bf16 v[2:5], v[200:203], v[232:235], v[2:5]
	v_mfma_f32_16x16x32_bf16 v[54:57], v[196:199], v[212:215], v[54:57]
	v_mfma_f32_16x16x32_bf16 v[50:53], v[204:207], v[212:215], v[50:53]
	v_mfma_f32_16x16x32_bf16 v[38:41], v[196:199], v[220:223], v[38:41]
	v_mfma_f32_16x16x32_bf16 v[34:37], v[204:207], v[220:223], v[34:37]
	v_mfma_f32_16x16x32_bf16 v[22:25], v[196:199], v[228:231], v[22:25]
	v_mfma_f32_16x16x32_bf16 v[18:21], v[204:207], v[228:231], v[18:21]
	v_mfma_f32_16x16x32_bf16 v[6:9], v[196:199], v[236:239], v[6:9]
	v_mfma_f32_16x16x32_bf16 v[2:5], v[204:207], v[236:239], v[2:5]
	s_setprio 0
	s_barrier
; #define PG8_STAGE(bufoff, gbase, voff) do { _Pragma("unroll") for (int _i = 0; _i < 2; ++_i) \
;         __builtin_amdgcn_global_load_lds((const unsigned*)((const char*)(gbase) + (voff)[_i]), (PG8_LAS unsigned*)(lds + (bufoff) + ldsw + _i * 8192), 16, 0, 0); } while (0)
; #define PG8_LDA(dst, b, h) do { _Pragma("unroll") for (int m = 0; m < 4; ++m) _Pragma("unroll") for (int k = 0; k < 2; ++k) dst[m][k] = *(const PG8_LAS bf16x8*)(lds + PG8_SA(b, h) + aoff + m * 2048 + k * 1024); } while (0)
; #define PG8_LDB(dst, b, h) do { _Pragma("unroll") for (int n = 0; n < 2; ++n) _Pragma("unroll") for (int k = 0; k < 2; ++k) dst[n][k] = *(const PG8_LAS bf16x8*)(lds + PG8_SB(b, h) + boff + n * 2048 + k * 1024); } while (0)
; #define PG8_MMA(ai, bj, At, Bt) do { __builtin_amdgcn_s_setprio(1); _Pragma("unroll") for (int m = 0; m < 4; ++m) _Pragma("unroll") for (int n = 0; n < 2; ++n) _Pragma("unroll") for (int k = 0; k < 2; ++k) \
;         acc[ai][bj][m][n] = __builtin_amdgcn_mfma_f32_16x16x32_bf16(Bt[n][k], At[m][k], acc[ai][bj][m][n], 0, 0, 0); __builtin_amdgcn_s_setprio(0); } while (0)
; #define PG8_WAIT_V(n) asm volatile("s_waitcnt vmcnt(" #n ")" ::: "memory")
; #define PG8_WAIT_L(n) asm volatile("s_waitcnt lgkmcnt(" #n ")" ::: "memory")
; #define PG8_BAR __builtin_amdgcn_s_barrier()
; #define PG8_SCHED __builtin_amdgcn_sched_barrier(0)
; template <class Epi, class Sched, bool ALIGN_EPI = false, bool SP2 = false>
; __device__ __forceinline__ void gemm_phase(PG8_LAS unsigned char* lds, const Gemm g, const Sched& S, const Epi& E) {
;     ...
;             PG8_LDB(B0, 1, 0); PG8_LDB(B1, 1, 1); PG8_SCHED; PG8_LDA(At, 1, 0); PG8_STAGE(PG8_SA(0, 1), a2 + hstep, voffA);
;             PG8_WAIT_V(8); PG8_WAIT_L(0); PG8_BAR; PG8_MMA(0, 0, At, B0); PG8_MMA(0, 1, At, B1); PG8_BAR; PG8_SCHED;
	s_add_i32 s48, 0, 0x18000
	v_add_u32_e32 v158, s48, v147
	s_add_i32 s49, 0, 0x1c000
	ds_read_b128 v[168:171], v158
	ds_read_b128 v[172:175], v158 offset:1024
	ds_read_b128 v[176:179], v158 offset:2048
	ds_read_b128 v[180:183], v158 offset:3072
	v_add_u32_e32 v158, s49, v147
	ds_read_b128 v[184:187], v158
	ds_read_b128 v[196:199], v158 offset:1024
	ds_read_b128 v[200:203], v158 offset:2048
	ds_read_b128 v[204:207], v158 offset:3072
	s_add_u32 s20, s20, 0x40000
	s_addc_u32 s21, s21, 0
	s_mov_b32 m0, s39
	v_lshl_add_u64 v[158:159], s[20:21], 0, v[136:137]
	ds_read_b128 v[208:211], v163 offset:32768
	ds_read_b128 v[212:215], v163 offset:33792
	ds_read_b128 v[216:219], v163 offset:34816
	ds_read_b128 v[220:223], v163 offset:35840
	ds_read_b128 v[224:227], v163 offset:36864
	ds_read_b128 v[228:231], v163 offset:37888
	ds_read_b128 v[232:235], v163 offset:38912
	ds_read_b128 v[236:239], v163 offset:39936
	global_load_lds_dwordx4 v[158:159], off
	v_lshl_add_u64 v[158:159], s[20:21], 0, v[132:133]
	s_mov_b32 m0, s40
	s_nop 0
	global_load_lds_dwordx4 v[158:159], off
	s_waitcnt vmcnt(8)
	s_waitcnt lgkmcnt(0)
	s_barrier
	s_setprio 1
	s_waitcnt lgkmcnt(0)
	v_mfma_f32_16x16x32_bf16 v[126:129], v[168:171], v[208:211], v[126:129]
	v_mfma_f32_16x16x32_bf16 v[122:125], v[176:179], v[208:211], v[122:125]
	v_mfma_f32_16x16x32_bf16 v[110:113], v[168:171], v[216:219], v[110:113]
	v_mfma_f32_16x16x32_bf16 v[106:109], v[176:179], v[216:219], v[106:109]
	v_mfma_f32_16x16x32_bf16 v[94:97], v[168:171], v[224:227], v[94:97]
	v_mfma_f32_16x16x32_bf16 v[90:93], v[176:179], v[224:227], v[90:93]
	v_mfma_f32_16x16x32_bf16 v[78:81], v[168:171], v[232:235], v[78:81]
	v_mfma_f32_16x16x32_bf16 v[74:77], v[176:179], v[232:235], v[74:77]
	v_mfma_f32_16x16x32_bf16 v[126:129], v[172:175], v[212:215], v[126:129]
	v_mfma_f32_16x16x32_bf16 v[122:125], v[180:183], v[212:215], v[122:125]
	v_mfma_f32_16x16x32_bf16 v[110:113], v[172:175], v[220:223], v[110:113]
	v_mfma_f32_16x16x32_bf16 v[106:109], v[180:183], v[220:223], v[106:109]
	v_mfma_f32_16x16x32_bf16 v[94:97], v[172:175], v[228:231], v[94:97]
	v_mfma_f32_16x16x32_bf16 v[90:93], v[180:183], v[228:231], v[90:93]
	v_mfma_f32_16x16x32_bf16 v[78:81], v[172:175], v[236:239], v[78:81]
	v_mfma_f32_16x16x32_bf16 v[74:77], v[180:183], v[236:239], v[74:77]
	s_setprio 0
	s_setprio 1
	v_mfma_f32_16x16x32_bf16 v[118:121], v[184:187], v[208:211], v[118:121]
	v_mfma_f32_16x16x32_bf16 v[114:117], v[200:203], v[208:211], v[114:117]
	v_mfma_f32_16x16x32_bf16 v[102:105], v[184:187], v[216:219], v[102:105]
	v_mfma_f32_16x16x32_bf16 v[98:101], v[200:203], v[216:219], v[98:101]
	v_mfma_f32_16x16x32_bf16 v[86:89], v[184:187], v[224:227], v[86:89]
	v_mfma_f32_16x16x32_bf16 v[82:85], v[200:203], v[224:227], v[82:85]
	v_mfma_f32_16x16x32_bf16 v[70:73], v[184:187], v[232:235], v[70:73]
	v_mfma_f32_16x16x32_bf16 v[66:69], v[200:203], v[232:235], v[66:69]
	v_mfma_f32_16x16x32_bf16 v[118:121], v[196:199], v[212:215], v[118:121]
	v_mfma_f32_16x16x32_bf16 v[114:117], v[204:207], v[212:215], v[114:117]
	v_mfma_f32_16x16x32_bf16 v[102:105], v[196:199], v[220:223], v[102:105]
	v_mfma_f32_16x16x32_bf16 v[98:101], v[204:207], v[220:223], v[98:101]
	v_mfma_f32_16x16x32_bf16 v[86:89], v[196:199], v[228:231], v[86:89]
	v_mfma_f32_16x16x32_bf16 v[82:85], v[204:207], v[228:231], v[82:85]
	v_mfma_f32_16x16x32_bf16 v[70:73], v[196:199], v[236:239], v[70:73]
	v_mfma_f32_16x16x32_bf16 v[66:69], v[204:207], v[236:239], v[66:69]
	s_setprio 0
	s_barrier
; #define PG8_STAGE(bufoff, gbase, voff) do { _Pragma("unroll") for (int _i = 0; _i < 2; ++_i) \
;         __builtin_amdgcn_global_load_lds((const unsigned*)((const char*)(gbase) + (voff)[_i]), (PG8_LAS unsigned*)(lds + (bufoff) + ldsw + _i * 8192), 16, 0, 0); } while (0)
; #define PG8_LDA(dst, b, h) do { _Pragma("unroll") for (int m = 0; m < 4; ++m) _Pragma("unroll") for (int k = 0; k < 2; ++k) dst[m][k] = *(const PG8_LAS bf16x8*)(lds + PG8_SA(b, h) + aoff + m * 2048 + k * 1024); } while (0)
; #define PG8_MMA(ai, bj, At, Bt) do { __builtin_amdgcn_s_setprio(1); _Pragma("unroll") for (int m = 0; m < 4; ++m) _Pragma("unroll") for (int n = 0; n < 2; ++n) _Pragma("unroll") for (int k = 0; k < 2; ++k) \
;         acc[ai][bj][m][n] = __builtin_amdgcn_mfma_f32_16x16x32_bf16(Bt[n][k], At[m][k], acc[ai][bj][m][n], 0, 0, 0); __builtin_amdgcn_s_setprio(0); } while (0)
; #define PG8_WAIT_V(n) asm volatile("s_waitcnt vmcnt(" #n ")" ::: "memory")
; #define PG8_WAIT_L(n) asm volatile("s_waitcnt lgkmcnt(" #n ")" ::: "memory")
; #define PG8_BAR __builtin_amdgcn_s_barrier()
; #define PG8_SCHED __builtin_amdgcn_sched_barrier(0)
; template <class Epi, class Sched, bool ALIGN_EPI = false, bool SP2 = false>
; __device__ __forceinline__ void gemm_phase(PG8_LAS unsigned char* lds, const Gemm g, const Sched& S, const Epi& E) {
;     ...
;         for (int t = 0; t < nt; t += 2) {
;     ...
;             PG8_LDA(At, 1, 1); PG8_STAGE(PG8_SB(1, 0), b3, voffB); PG8_STAGE(PG8_SB(1, 1), b3 + hstep, voffB); PG8_STAGE(PG8_SA(1, 0), a3, voffA);
;             PG8_WAIT_V(8); PG8_WAIT_L(0); PG8_BAR; PG8_MMA(1, 0, At, B0); PG8_MMA(1, 1, At, B1); PG8_BAR; PG8_SCHED;
	s_add_i32 s20, s48, s30
	v_lshl_add_u64 v[150:151], v[150:151], 0, s[16:17]
	s_mov_b32 m0, s20
	ds_read_b128 v[208:211], v163 offset:49152
	ds_read_b128 v[212:215], v163 offset:50176
	ds_read_b128 v[216:219], v163 offset:51200
	ds_read_b128 v[220:223], v163 offset:52224
	ds_read_b128 v[224:227], v163 offset:53248
	ds_read_b128 v[228:231], v163 offset:54272
	ds_read_b128 v[232:235], v163 offset:55296
	ds_read_b128 v[236:239], v163 offset:56320
	global_load_lds_dwordx4 v[150:151], off
	s_add_i32 m0, s20, 0x2000
	s_add_u32 s4, s4, 0x40080
	v_lshl_add_u64 v[150:151], v[152:153], 0, s[16:17]
	s_addc_u32 s5, s5, 0
	s_add_i32 s20, s49, s30
	global_load_lds_dwordx4 v[150:151], off
	v_lshl_add_u64 v[150:151], s[4:5], 0, v[134:135]
	s_mov_b32 m0, s20
	s_nop 0
	global_load_lds_dwordx4 v[150:151], off
	v_lshl_add_u64 v[150:151], s[4:5], 0, v[130:131]
	s_add_i32 m0, s20, 0x2000
	s_nop 0
	global_load_lds_dwordx4 v[150:151], off
	v_lshl_add_u64 v[150:151], v[154:155], 0, s[16:17]
	s_mov_b32 m0, s42
	s_nop 0
	global_load_lds_dwordx4 v[150:151], off
	v_lshl_add_u64 v[150:151], v[156:157], 0, s[16:17]
	s_mov_b32 m0, s43
	s_nop 0
	global_load_lds_dwordx4 v[150:151], off
	s_waitcnt vmcnt(8)
	s_waitcnt lgkmcnt(0)
	s_barrier
	s_setprio 1
	s_waitcnt lgkmcnt(0)
	v_mfma_f32_16x16x32_bf16 v[62:65], v[168:171], v[208:211], v[62:65]
	v_mfma_f32_16x16x32_bf16 v[58:61], v[176:179], v[208:211], v[58:61]
	v_mfma_f32_16x16x32_bf16 v[46:49], v[168:171], v[216:219], v[46:49]
	v_mfma_f32_16x16x32_bf16 v[42:45], v[176:179], v[216:219], v[42:45]
	v_mfma_f32_16x16x32_bf16 v[30:33], v[168:171], v[224:227], v[30:33]
	v_mfma_f32_16x16x32_bf16 v[26:29], v[176:179], v[224:227], v[26:29]
	v_mfma_f32_16x16x32_bf16 v[14:17], v[168:171], v[232:235], v[14:17]
	v_mfma_f32_16x16x32_bf16 v[10:13], v[176:179], v[232:235], v[10:13]
	v_mfma_f32_16x16x32_bf16 v[62:65], v[172:175], v[212:215], v[62:65]
	v_mfma_f32_16x16x32_bf16 v[58:61], v[180:183], v[212:215], v[58:61]
	v_mfma_f32_16x16x32_bf16 v[46:49], v[172:175], v[220:223], v[46:49]
	v_mfma_f32_16x16x32_bf16 v[42:45], v[180:183], v[220:223], v[42:45]
	v_mfma_f32_16x16x32_bf16 v[30:33], v[172:175], v[228:231], v[30:33]
	v_mfma_f32_16x16x32_bf16 v[26:29], v[180:183], v[228:231], v[26:29]
	v_mfma_f32_16x16x32_bf16 v[14:17], v[172:175], v[236:239], v[14:17]
	v_mfma_f32_16x16x32_bf16 v[10:13], v[180:183], v[236:239], v[10:13]
	s_setprio 0
	s_setprio 1
	v_mfma_f32_16x16x32_bf16 v[54:57], v[184:187], v[208:211], v[54:57]
	v_mfma_f32_16x16x32_bf16 v[50:53], v[200:203], v[208:211], v[50:53]
	v_mfma_f32_16x16x32_bf16 v[38:41], v[184:187], v[216:219], v[38:41]
	v_mfma_f32_16x16x32_bf16 v[34:37], v[200:203], v[216:219], v[34:37]
	v_mfma_f32_16x16x32_bf16 v[22:25], v[184:187], v[224:227], v[22:25]
	v_mfma_f32_16x16x32_bf16 v[18:21], v[200:203], v[224:227], v[18:21]
	v_mfma_f32_16x16x32_bf16 v[6:9], v[184:187], v[232:235], v[6:9]
	v_mfma_f32_16x16x32_bf16 v[2:5], v[200:203], v[232:235], v[2:5]
	v_mfma_f32_16x16x32_bf16 v[54:57], v[196:199], v[212:215], v[54:57]
	v_mfma_f32_16x16x32_bf16 v[50:53], v[204:207], v[212:215], v[50:53]
	v_mfma_f32_16x16x32_bf16 v[38:41], v[196:199], v[220:223], v[38:41]
	v_mfma_f32_16x16x32_bf16 v[34:37], v[204:207], v[220:223], v[34:37]
	v_mfma_f32_16x16x32_bf16 v[22:25], v[196:199], v[228:231], v[22:25]
	v_mfma_f32_16x16x32_bf16 v[18:21], v[204:207], v[228:231], v[18:21]
	v_mfma_f32_16x16x32_bf16 v[6:9], v[196:199], v[236:239], v[6:9]
	v_mfma_f32_16x16x32_bf16 v[2:5], v[204:207], v[236:239], v[2:5]
	s_setprio 0
	s_barrier
	s_add_i32 s47, s47, 2
	s_add_u32 s2, s2, 0x100
	s_addc_u32 s3, s3, 0
	s_add_u32 s45, s45, 0x100
	s_addc_u32 s46, s46, 0
	s_cmp_gt_u32 s47, 13
	s_cbranch_scc0 .LBB0_126
	s_and_b64 vcc, exec, s[10:11]
	s_cbranch_vccz .LBB0_129
	s_barrier

; __global__ void __launch_bounds__(NTHREADS, 2) fwd_megakernel(Args A) {
	.amdhsa_kernel _Z14fwd_megakernel4Args
		.amdhsa_group_segment_fixed_size 0
		.amdhsa_private_segment_fixed_size 0
		.amdhsa_kernarg_size 400
		.amdhsa_user_sgpr_count 2
		.amdhsa_user_sgpr_dispatch_ptr 0
		.amdhsa_user_sgpr_queue_ptr 0
		.amdhsa_user_sgpr_kernarg_segment_ptr 1
		.amdhsa_user_sgpr_dispatch_id 0
		.amdhsa_user_sgpr_kernarg_preload_length 0
		.amdhsa_user_sgpr_kernarg_preload_offset 0
		.amdhsa_user_sgpr_private_segment_size 0
		.amdhsa_uses_dynamic_stack 0
		.amdhsa_enable_private_segment 0
		.amdhsa_system_sgpr_workgroup_id_x 1
		.amdhsa_system_sgpr_workgroup_id_y 0
		.amdhsa_system_sgpr_workgroup_id_z 0
		.amdhsa_system_sgpr_workgroup_info 0
		.amdhsa_system_vgpr_workitem_id 2
		.amdhsa_next_free_vgpr 256
		.amdhsa_next_free_sgpr 102
		.amdhsa_accum_offset 256
		.amdhsa_reserve_vcc 1
		.amdhsa_float_round_mode_32 0
		.amdhsa_float_round_mode_16_64 0
		.amdhsa_float_denorm_mode_32 3
		.amdhsa_float_denorm_mode_16_64 3
		.amdhsa_dx10_clamp 1
		.amdhsa_ieee_mode 1
		.amdhsa_fp16_overflow 0
		.amdhsa_tg_split 0
		.amdhsa_exception_fp_ieee_invalid_op 0
		.amdhsa_exception_fp_denorm_src 0
		.amdhsa_exception_fp_ieee_div_zero 0
		.amdhsa_exception_fp_ieee_overflow 0
		.amdhsa_exception_fp_ieee_underflow 0
		.amdhsa_exception_fp_ieee_inexact 0
		.amdhsa_exception_int_div_zero 0
	.end_amdhsa_kernel

; __global__ void __launch_bounds__(NTHREADS, 2) fwd_megakernel(Args A) {
amdhsa.kernels:
  - .agpr_count:     0
    .args:
      - .offset:         0
        .size:           144
        .value_kind:     by_value
      - .offset:         144
        .size:           4
        .value_kind:     hidden_block_count_x
      - .offset:         148
        .size:           4
        .value_kind:     hidden_block_count_y
      - .offset:         152
        .size:           4
        .value_kind:     hidden_block_count_z
      - .offset:         156
        .size:           2
        .value_kind:     hidden_group_size_x
      - .offset:         158
        .size:           2
        .value_kind:     hidden_group_size_y
      - .offset:         160
        .size:           2
        .value_kind:     hidden_group_size_z
      - .offset:         162
        .size:           2
        .value_kind:     hidden_remainder_x
      - .offset:         164
        .size:           2
        .value_kind:     hidden_remainder_y
      - .offset:         166
        .size:           2
        .value_kind:     hidden_remainder_z
      - .offset:         184
        .size:           8
        .value_kind:     hidden_global_offset_x
      - .offset:         192
        .size:           8
        .value_kind:     hidden_global_offset_y
      - .offset:         200
        .size:           8
        .value_kind:     hidden_global_offset_z
      - .offset:         208
        .size:           2
        .value_kind:     hidden_grid_dims
      - .offset:         232
        .size:           8
        .value_kind:     hidden_multigrid_sync_arg
      - .offset:         264
        .size:           4
        .value_kind:     hidden_dynamic_lds_size
    .group_segment_fixed_size: 0
    .kernarg_segment_align: 8
    .kernarg_segment_size: 400
    .language:       OpenCL C
    .language_version:
      - 2
      - 0
    .max_flat_workgroup_size: 512
    .name:           _Z14fwd_megakernel4Args
    .private_segment_fixed_size: 0
    .sgpr_count:     108
    .sgpr_spill_count: 318
    .symbol:         _Z14fwd_megakernel4Args.kd
    .uniform_work_group_size: 1
    .uses_dynamic_stack: false
    .vgpr_count:     256
    .vgpr_spill_count: 0
    .wavefront_size: 64
